# MLA loop emitted once per wave class: waves 4-7 no longer load/write the shared rope-key rows that waves 0-3 already stage (2 instead of 3 staging loads per tile)
# speedup vs baseline: 1.0226x; 1.0226x over previous
.Lmla_p_nomask:
	v_max3_f32 v251, v64, v65, v66
	v_max3_f32 v251, v251, v67, v68
	v_max3_f32 v251, v251, v69, v70
	v_max3_f32 v251, v251, v71, v72
	v_max3_f32 v251, v251, v73, v74
	v_max3_f32 v251, v251, v75, v76
	v_max3_f32 v251, v251, v77, v78
	v_max_f32_e32 v251, v251, v79
	v_max3_f32 v252, v80, v81, v82
	v_max3_f32 v252, v252, v83, v84
	v_max3_f32 v252, v252, v85, v86
	v_max3_f32 v252, v252, v87, v88
	v_max3_f32 v252, v252, v89, v90
	v_max3_f32 v252, v252, v91, v92
	v_max3_f32 v252, v252, v93, v94
	v_max_f32_e32 v252, v252, v95
	v_max_f32_e32 v251, v251, v252
	v_mov_b32_e32 v252, v251
	s_nop 1
	v_permlane32_swap_b32_e32 v251, v252
	v_max_f32_e32 v251, v251, v252
	v_mov_b32_e32 v212, v251
	v_sub_f32_e32 v64, v64, v251
	v_sub_f32_e32 v65, v65, v251
	v_sub_f32_e32 v66, v66, v251
	v_sub_f32_e32 v67, v67, v251
	v_sub_f32_e32 v68, v68, v251
	v_sub_f32_e32 v69, v69, v251
	v_sub_f32_e32 v70, v70, v251
	v_sub_f32_e32 v71, v71, v251
	v_sub_f32_e32 v72, v72, v251
	v_sub_f32_e32 v73, v73, v251
	v_sub_f32_e32 v74, v74, v251
	v_sub_f32_e32 v75, v75, v251
	v_sub_f32_e32 v76, v76, v251
	v_sub_f32_e32 v77, v77, v251
	v_sub_f32_e32 v78, v78, v251
	v_sub_f32_e32 v79, v79, v251
	v_sub_f32_e32 v80, v80, v251
	v_sub_f32_e32 v81, v81, v251
	v_sub_f32_e32 v82, v82, v251
	v_sub_f32_e32 v83, v83, v251
	v_sub_f32_e32 v84, v84, v251
	v_sub_f32_e32 v85, v85, v251
	v_sub_f32_e32 v86, v86, v251
	v_sub_f32_e32 v87, v87, v251
	v_sub_f32_e32 v88, v88, v251
	v_sub_f32_e32 v89, v89, v251
	v_sub_f32_e32 v90, v90, v251
	v_sub_f32_e32 v91, v91, v251
	v_sub_f32_e32 v92, v92, v251
	v_sub_f32_e32 v93, v93, v251
	v_sub_f32_e32 v94, v94, v251
	v_sub_f32_e32 v95, v95, v251
	v_xor_b32_e32 v48, 0x80000000, v251
	v_mov_b32_e32 v49, v48
	v_mov_b32_e32 v50, v48
	v_mov_b32_e32 v51, v48
	v_mov_b32_e32 v52, v48
	v_mov_b32_e32 v53, v48
	v_mov_b32_e32 v54, v48
	v_mov_b32_e32 v55, v48
	v_mov_b32_e32 v56, v48
	v_mov_b32_e32 v57, v48
	v_mov_b32_e32 v58, v48
	v_mov_b32_e32 v59, v48
	v_mov_b32_e32 v60, v48
	v_mov_b32_e32 v61, v48
	v_mov_b32_e32 v62, v48
	v_mov_b32_e32 v63, v48
	s_waitcnt lgkmcnt(0)
	s_barrier
	s_cmp_lt_u32 s39, 4
	s_cbranch_scc0 .Lmla_loopb

.Lmla_loopb:
.Lmla_it0b:
	s_add_i32 s42, s65, 3
	s_min_u32 s42, s42, s44
	s_lshl_b64 s[6:7], s[42:43], 17
	v_lshl_add_u64 v[242:243], v[190:191], 0, s[6:7]
	s_lshl_b64 s[6:7], s[42:43], 12
	v_lshl_add_u64 v[244:245], v[194:195], 0, s[6:7]
	s_add_i32 s42, s65, 2
	s_min_u32 s42, s42, s44
	s_lshl_b64 s[6:7], s[42:43], 17
	v_lshl_add_u64 v[246:247], v[192:193], 0, s[6:7]
	global_load_dwordx4 v[6:9], v[242:243], off
	global_load_dwordx4 v[10:13], v[246:247], off
	s_cmp_ge_u32 s65, s45
	s_cbranch_scc1 .Lmla_skip0b
	s_add_i32 s41, s65, 1
	s_cmp_ge_u32 s41, s64
	s_cselect_b32 s7, 1, 0
	s_cmp_lt_u32 s41, s45
	s_cselect_b32 s26, 1, 0
	s_and_b32 s56, s7, s26
	s_lshl_b32 s27, s41, 6
	ds_read_b128 v[164:167], v210 offset:25600
	ds_read_b128 v[168:171], v210 offset:25632
	ds_read_b128 v[172:175], v210 offset:25664
	ds_read_b128 v[214:217], v210 offset:25696
	ds_read_b128 v[218:221], v210 offset:25728
	ds_read_b128 v[222:225], v210 offset:25760
	s_setprio 3
	v_exp_f32_e32 v64, v64
	v_exp_f32_e32 v65, v65
	v_exp_f32_e32 v66, v66
	v_exp_f32_e32 v67, v67
	s_waitcnt lgkmcnt(5)
	v_mfma_f32_32x32x16_bf16 v[132:147], v[164:167], v[96:99], v[48:63]
	ds_read_b128 v[164:167], v210 offset:32256
	v_add_f32_e32 v14, v64, v65
	v_add_f32_e32 v15, v66, v67
	v_exp_f32_e32 v68, v68
	v_exp_f32_e32 v69, v69
	s_waitcnt lgkmcnt(5)
	v_mfma_f32_32x32x16_bf16 v[132:147], v[168:171], v[100:103], v[132:147]
	ds_read_b128 v[168:171], v210 offset:32288
	v_exp_f32_e32 v70, v70
	v_exp_f32_e32 v71, v71
	v_add_f32_e32 v14, v14, v15
	v_add_f32_e32 v15, v68, v69
	s_waitcnt lgkmcnt(5)
	v_mfma_f32_32x32x16_bf16 v[132:147], v[172:175], v[104:107], v[132:147]
	ds_read_b128 v[172:175], v210 offset:32320
	v_add_f32_e32 v213, v70, v71
	v_cvt_pk_bf16_f32 v64, v64, v65
	v_cvt_pk_bf16_f32 v65, v66, v67
	v_cvt_pk_bf16_f32 v66, v68, v69
	v_cvt_pk_bf16_f32 v67, v70, v71
	s_waitcnt lgkmcnt(5)
	v_mfma_f32_32x32x16_bf16 v[132:147], v[214:217], v[108:111], v[132:147]
	ds_read_b128 v[214:217], v210 offset:32352
	v_exp_f32_e32 v72, v72
	v_exp_f32_e32 v73, v73
	v_exp_f32_e32 v74, v74
	v_exp_f32_e32 v75, v75
	s_waitcnt lgkmcnt(5)
	v_mfma_f32_32x32x16_bf16 v[132:147], v[218:221], v[112:115], v[132:147]
	ds_read_b128 v[218:221], v210 offset:32384
	v_add_f32_e32 v14, v14, v15
	v_add_f32_e32 v14, v14, v213
	v_exp_f32_e32 v76, v76
	v_exp_f32_e32 v77, v77
	s_setprio 2
	s_waitcnt lgkmcnt(5)
	v_mfma_f32_32x32x16_bf16 v[132:147], v[222:225], v[116:119], v[132:147]
	ds_read_b128 v[222:225], v210 offset:32416
	v_exp_f32_e32 v78, v78
	v_exp_f32_e32 v79, v79
	v_add_f32_e32 v15, v72, v73
	v_add_f32_e32 v213, v74, v75
	s_waitcnt lgkmcnt(5)
	v_mfma_f32_32x32x16_bf16 v[148:163], v[164:167], v[96:99], v[48:63]
	ds_read_b64_tr_b16 v[226:227], v211 offset:13312
	ds_read_b64_tr_b16 v[228:229], v211 offset:14848
	v_add_f32_e32 v248, v76, v77
	v_add_f32_e32 v249, v78, v79
	v_cvt_pk_bf16_f32 v68, v72, v73
	v_cvt_pk_bf16_f32 v69, v74, v75
	v_cvt_pk_bf16_f32 v70, v76, v77
	v_cvt_pk_bf16_f32 v71, v78, v79
	s_waitcnt lgkmcnt(6)
	v_mfma_f32_32x32x16_bf16 v[148:163], v[168:171], v[100:103], v[148:163]
	ds_read_b64_tr_b16 v[230:231], v211 offset:13376
	ds_read_b64_tr_b16 v[232:233], v211 offset:14912
	v_add_f32_e32 v15, v15, v213
	v_add_f32_e32 v248, v248, v249
	v_exp_f32_e32 v80, v80
	v_exp_f32_e32 v81, v81
	s_waitcnt lgkmcnt(7)
	v_mfma_f32_32x32x16_bf16 v[148:163], v[172:175], v[104:107], v[148:163]
	ds_read_b64_tr_b16 v[234:235], v211 offset:16384
	ds_read_b64_tr_b16 v[236:237], v211 offset:17920
	v_exp_f32_e32 v82, v82
	v_exp_f32_e32 v83, v83
	v_add_f32_e32 v14, v14, v15
	v_add_f32_e32 v14, v14, v248
	s_waitcnt lgkmcnt(8)
	v_mfma_f32_32x32x16_bf16 v[148:163], v[214:217], v[108:111], v[148:163]
	ds_read_b64_tr_b16 v[238:239], v211 offset:16448
	ds_read_b64_tr_b16 v[240:241], v211 offset:17984
	v_add_f32_e32 v15, v80, v81
	v_add_f32_e32 v213, v82, v83
	v_exp_f32_e32 v84, v84
	v_exp_f32_e32 v85, v85
	s_setprio 1
	s_waitcnt lgkmcnt(9)
	v_mfma_f32_32x32x16_bf16 v[148:163], v[218:221], v[112:115], v[148:163]
	v_exp_f32_e32 v86, v86
	v_exp_f32_e32 v87, v87
	v_add_f32_e32 v15, v15, v213
	v_add_f32_e32 v213, v84, v85
	s_waitcnt lgkmcnt(8)
	v_mfma_f32_32x32x16_bf16 v[148:163], v[222:225], v[116:119], v[148:163]
	v_add_f32_e32 v248, v86, v87
	v_cvt_pk_bf16_f32 v80, v80, v81
	v_cvt_pk_bf16_f32 v81, v82, v83
	v_cvt_pk_bf16_f32 v82, v84, v85
	v_cvt_pk_bf16_f32 v83, v86, v87
	s_waitcnt lgkmcnt(6)
	v_mfma_f32_32x32x16_bf16 v[32:47], v[226:229], v[64:67], v[32:47]
	ds_read_b64_tr_b16 v[226:227], v211 offset:19456
	ds_read_b64_tr_b16 v[228:229], v211 offset:20992
	v_exp_f32_e32 v88, v88
	v_exp_f32_e32 v89, v89
	v_exp_f32_e32 v90, v90
	v_exp_f32_e32 v91, v91
	s_waitcnt lgkmcnt(6)
	v_mfma_f32_32x32x16_bf16 v[16:31], v[230:233], v[64:67], v[16:31]
	ds_read_b64_tr_b16 v[230:231], v211 offset:19520
	ds_read_b64_tr_b16 v[232:233], v211 offset:21056
	v_add_f32_e32 v213, v213, v248
	v_add_f32_e32 v15, v15, v213
	v_exp_f32_e32 v92, v92
	v_exp_f32_e32 v93, v93
	s_waitcnt lgkmcnt(6)
	v_mfma_f32_32x32x16_bf16 v[32:47], v[234:237], v[68:71], v[32:47]
	ds_read_b64_tr_b16 v[234:235], v211 offset:22528
	ds_read_b64_tr_b16 v[236:237], v211 offset:24064
	v_exp_f32_e32 v94, v94
	v_exp_f32_e32 v95, v95
	v_add_f32_e32 v213, v88, v89
	v_add_f32_e32 v248, v90, v91
	s_setprio 0
	s_waitcnt lgkmcnt(6)
	v_mfma_f32_32x32x16_bf16 v[16:31], v[238:241], v[68:71], v[16:31]
	ds_read_b64_tr_b16 v[238:239], v211 offset:22592
	ds_read_b64_tr_b16 v[240:241], v211 offset:24128
	s_cmp_lg_u32 s56, 0
	s_cbranch_scc1 .Lmla_mask0b
.Lmla_maskret0b:
	v_add_f32_e32 v249, v92, v93
	v_add_f32_e32 v250, v94, v95
	v_cvt_pk_bf16_f32 v84, v88, v89
	v_cvt_pk_bf16_f32 v85, v90, v91
	v_cvt_pk_bf16_f32 v86, v92, v93
	v_cvt_pk_bf16_f32 v87, v94, v95
	s_waitcnt lgkmcnt(6)
	v_mfma_f32_32x32x16_bf16 v[32:47], v[226:229], v[80:83], v[32:47]
	v_add_f32_e32 v213, v213, v248
	v_add_f32_e32 v249, v249, v250
	v_add_f32_e32 v14, v14, v15
	v_max3_f32 v251, v132, v133, v134
	v_max3_f32 v251, v251, v135, v136
	s_waitcnt lgkmcnt(4)
	v_mfma_f32_32x32x16_bf16 v[16:31], v[230:233], v[80:83], v[16:31]
	s_waitcnt vmcnt(2)
	ds_write_b128 v205, v[120:123] offset:0
	ds_write_b128 v206, v[124:127] offset:38912
	v_add_f32_e32 v213, v213, v249
	v_add_f32_e32 v14, v14, v213
	v_add_f32_e32 v209, v209, v14
	v_max3_f32 v251, v251, v137, v138
	v_max3_f32 v251, v251, v139, v140
	v_max3_f32 v251, v251, v141, v142
	s_waitcnt lgkmcnt(4)
	v_mfma_f32_32x32x16_bf16 v[32:47], v[234:237], v[84:87], v[32:47]
	v_max3_f32 v251, v251, v143, v144
	v_max3_f32 v251, v251, v145, v146
	v_max_f32_e32 v251, v251, v147
	v_max3_f32 v252, v148, v149, v150
	v_max3_f32 v252, v252, v151, v152
	s_waitcnt lgkmcnt(2)
	v_mfma_f32_32x32x16_bf16 v[16:31], v[238:241], v[84:87], v[16:31]
	v_max3_f32 v252, v252, v153, v154
	v_max3_f32 v252, v252, v155, v156
	v_max3_f32 v252, v252, v157, v158
	v_max3_f32 v252, v252, v159, v160
	v_max3_f32 v252, v252, v161, v162
	v_max_f32_e32 v252, v252, v163
	v_max_f32_e32 v251, v251, v252
	v_mov_b32_e32 v252, v251
	s_nop 1
	v_permlane32_swap_b32_e32 v251, v252
	v_max_f32_e32 v251, v251, v252
	v_cmp_lt_f32_e32 vcc, 0x41000000, v251
	s_cmp_lg_u32 s26, 0
	s_cbranch_scc0 .Lmla_nr0b
	s_cbranch_vccnz .Lmla_rare0b

.Lmla_end0b:
.Lmla_it1b:
	s_add_i32 s66, s65, 1
	s_add_i32 s42, s66, 3
	s_min_u32 s42, s42, s44
	s_lshl_b64 s[6:7], s[42:43], 17
	v_lshl_add_u64 v[242:243], v[190:191], 0, s[6:7]
	s_lshl_b64 s[6:7], s[42:43], 12
	v_lshl_add_u64 v[244:245], v[194:195], 0, s[6:7]
	s_add_i32 s42, s66, 2
	s_min_u32 s42, s42, s44
	s_lshl_b64 s[6:7], s[42:43], 17
	v_lshl_add_u64 v[246:247], v[192:193], 0, s[6:7]
	global_load_dwordx4 v[120:123], v[242:243], off
	global_load_dwordx4 v[124:127], v[246:247], off
	s_cmp_ge_u32 s66, s45
	s_cbranch_scc1 .Lmla_skip1b
	s_add_i32 s41, s66, 1
	s_cmp_ge_u32 s41, s64
	s_cselect_b32 s7, 1, 0
	s_cmp_lt_u32 s41, s45
	s_cselect_b32 s26, 1, 0
	s_and_b32 s56, s7, s26
	s_lshl_b32 s27, s41, 6
	ds_read_b128 v[164:167], v210 offset:0
	ds_read_b128 v[168:171], v210 offset:32
	ds_read_b128 v[172:175], v210 offset:64
	ds_read_b128 v[214:217], v210 offset:96
	ds_read_b128 v[218:221], v210 offset:128
	ds_read_b128 v[222:225], v210 offset:160
	s_setprio 3
	v_exp_f32_e32 v132, v132
	v_exp_f32_e32 v133, v133
	v_exp_f32_e32 v134, v134
	v_exp_f32_e32 v135, v135
	s_waitcnt lgkmcnt(5)
	v_mfma_f32_32x32x16_bf16 v[64:79], v[164:167], v[96:99], v[48:63]
	ds_read_b128 v[164:167], v210 offset:6656
	v_add_f32_e32 v14, v132, v133
	v_add_f32_e32 v15, v134, v135
	v_exp_f32_e32 v136, v136
	v_exp_f32_e32 v137, v137
	s_waitcnt lgkmcnt(5)
	v_mfma_f32_32x32x16_bf16 v[64:79], v[168:171], v[100:103], v[64:79]
	ds_read_b128 v[168:171], v210 offset:6688
	v_exp_f32_e32 v138, v138
	v_exp_f32_e32 v139, v139
	v_add_f32_e32 v14, v14, v15
	v_add_f32_e32 v15, v136, v137
	s_waitcnt lgkmcnt(5)
	v_mfma_f32_32x32x16_bf16 v[64:79], v[172:175], v[104:107], v[64:79]
	ds_read_b128 v[172:175], v210 offset:6720
	v_add_f32_e32 v213, v138, v139
	v_cvt_pk_bf16_f32 v132, v132, v133
	v_cvt_pk_bf16_f32 v133, v134, v135
	v_cvt_pk_bf16_f32 v134, v136, v137
	v_cvt_pk_bf16_f32 v135, v138, v139
	s_waitcnt lgkmcnt(5)
	v_mfma_f32_32x32x16_bf16 v[64:79], v[214:217], v[108:111], v[64:79]
	ds_read_b128 v[214:217], v210 offset:6752
	v_exp_f32_e32 v140, v140
	v_exp_f32_e32 v141, v141
	v_exp_f32_e32 v142, v142
	v_exp_f32_e32 v143, v143
	s_waitcnt lgkmcnt(5)
	v_mfma_f32_32x32x16_bf16 v[64:79], v[218:221], v[112:115], v[64:79]
	ds_read_b128 v[218:221], v210 offset:6784
	v_add_f32_e32 v14, v14, v15
	v_add_f32_e32 v14, v14, v213
	v_exp_f32_e32 v144, v144
	v_exp_f32_e32 v145, v145
	s_setprio 2
	s_waitcnt lgkmcnt(5)
	v_mfma_f32_32x32x16_bf16 v[64:79], v[222:225], v[116:119], v[64:79]
	ds_read_b128 v[222:225], v210 offset:6816
	v_exp_f32_e32 v146, v146
	v_exp_f32_e32 v147, v147
	v_add_f32_e32 v15, v140, v141
	v_add_f32_e32 v213, v142, v143
	s_waitcnt lgkmcnt(5)
	v_mfma_f32_32x32x16_bf16 v[80:95], v[164:167], v[96:99], v[48:63]
	ds_read_b64_tr_b16 v[226:227], v211 offset:38912
	ds_read_b64_tr_b16 v[228:229], v211 offset:40448
	v_add_f32_e32 v248, v144, v145
	v_add_f32_e32 v249, v146, v147
	v_cvt_pk_bf16_f32 v136, v140, v141
	v_cvt_pk_bf16_f32 v137, v142, v143
	v_cvt_pk_bf16_f32 v138, v144, v145
	v_cvt_pk_bf16_f32 v139, v146, v147
	s_waitcnt lgkmcnt(6)
	v_mfma_f32_32x32x16_bf16 v[80:95], v[168:171], v[100:103], v[80:95]
	ds_read_b64_tr_b16 v[230:231], v211 offset:38976
	ds_read_b64_tr_b16 v[232:233], v211 offset:40512
	v_add_f32_e32 v15, v15, v213
	v_add_f32_e32 v248, v248, v249
	v_exp_f32_e32 v148, v148
	v_exp_f32_e32 v149, v149
	s_waitcnt lgkmcnt(7)
	v_mfma_f32_32x32x16_bf16 v[80:95], v[172:175], v[104:107], v[80:95]
	ds_read_b64_tr_b16 v[234:235], v211 offset:41984
	ds_read_b64_tr_b16 v[236:237], v211 offset:43520
	v_exp_f32_e32 v150, v150
	v_exp_f32_e32 v151, v151
	v_add_f32_e32 v14, v14, v15
	v_add_f32_e32 v14, v14, v248
	s_waitcnt lgkmcnt(8)
	v_mfma_f32_32x32x16_bf16 v[80:95], v[214:217], v[108:111], v[80:95]
	ds_read_b64_tr_b16 v[238:239], v211 offset:42048
	ds_read_b64_tr_b16 v[240:241], v211 offset:43584
	v_add_f32_e32 v15, v148, v149
	v_add_f32_e32 v213, v150, v151
	v_exp_f32_e32 v152, v152
	v_exp_f32_e32 v153, v153
	s_setprio 1
	s_waitcnt lgkmcnt(9)
	v_mfma_f32_32x32x16_bf16 v[80:95], v[218:221], v[112:115], v[80:95]
	v_exp_f32_e32 v154, v154
	v_exp_f32_e32 v155, v155
	v_add_f32_e32 v15, v15, v213
	v_add_f32_e32 v213, v152, v153
	s_waitcnt lgkmcnt(8)
	v_mfma_f32_32x32x16_bf16 v[80:95], v[222:225], v[116:119], v[80:95]
	v_add_f32_e32 v248, v154, v155
	v_cvt_pk_bf16_f32 v148, v148, v149
	v_cvt_pk_bf16_f32 v149, v150, v151
	v_cvt_pk_bf16_f32 v150, v152, v153
	v_cvt_pk_bf16_f32 v151, v154, v155
	s_waitcnt lgkmcnt(6)
	v_mfma_f32_32x32x16_bf16 v[32:47], v[226:229], v[132:135], v[32:47]
	ds_read_b64_tr_b16 v[226:227], v211 offset:45056
	ds_read_b64_tr_b16 v[228:229], v211 offset:46592
	v_exp_f32_e32 v156, v156
	v_exp_f32_e32 v157, v157
	v_exp_f32_e32 v158, v158
	v_exp_f32_e32 v159, v159
	s_waitcnt lgkmcnt(6)
	v_mfma_f32_32x32x16_bf16 v[16:31], v[230:233], v[132:135], v[16:31]
	ds_read_b64_tr_b16 v[230:231], v211 offset:45120
	ds_read_b64_tr_b16 v[232:233], v211 offset:46656
	v_add_f32_e32 v213, v213, v248
	v_add_f32_e32 v15, v15, v213
	v_exp_f32_e32 v160, v160
	v_exp_f32_e32 v161, v161
	s_waitcnt lgkmcnt(6)
	v_mfma_f32_32x32x16_bf16 v[32:47], v[234:237], v[136:139], v[32:47]
	ds_read_b64_tr_b16 v[234:235], v211 offset:48128
	ds_read_b64_tr_b16 v[236:237], v211 offset:49664
	v_exp_f32_e32 v162, v162
	v_exp_f32_e32 v163, v163
	v_add_f32_e32 v213, v156, v157
	v_add_f32_e32 v248, v158, v159
	s_setprio 0
	s_waitcnt lgkmcnt(6)
	v_mfma_f32_32x32x16_bf16 v[16:31], v[238:241], v[136:139], v[16:31]
	ds_read_b64_tr_b16 v[238:239], v211 offset:48192
	ds_read_b64_tr_b16 v[240:241], v211 offset:49728
	s_cmp_lg_u32 s56, 0
	s_cbranch_scc1 .Lmla_mask1b
.Lmla_maskret1b:
	v_add_f32_e32 v249, v160, v161
	v_add_f32_e32 v250, v162, v163
	v_cvt_pk_bf16_f32 v152, v156, v157
	v_cvt_pk_bf16_f32 v153, v158, v159
	v_cvt_pk_bf16_f32 v154, v160, v161
	v_cvt_pk_bf16_f32 v155, v162, v163
	s_waitcnt lgkmcnt(6)
	v_mfma_f32_32x32x16_bf16 v[32:47], v[226:229], v[148:151], v[32:47]
	v_add_f32_e32 v213, v213, v248
	v_add_f32_e32 v249, v249, v250
	v_add_f32_e32 v14, v14, v15
	v_max3_f32 v251, v64, v65, v66
	v_max3_f32 v251, v251, v67, v68
	s_waitcnt lgkmcnt(4)
	v_mfma_f32_32x32x16_bf16 v[16:31], v[230:233], v[148:151], v[16:31]
	s_waitcnt vmcnt(2)
	ds_write_b128 v205, v[6:9] offset:25600
	ds_write_b128 v206, v[10:13] offset:13312
	v_add_f32_e32 v213, v213, v249
	v_add_f32_e32 v14, v14, v213
	v_add_f32_e32 v209, v209, v14
	v_max3_f32 v251, v251, v69, v70
	v_max3_f32 v251, v251, v71, v72
	v_max3_f32 v251, v251, v73, v74
	s_waitcnt lgkmcnt(4)
	v_mfma_f32_32x32x16_bf16 v[32:47], v[234:237], v[152:155], v[32:47]
	v_max3_f32 v251, v251, v75, v76
	v_max3_f32 v251, v251, v77, v78
	v_max_f32_e32 v251, v251, v79
	v_max3_f32 v252, v80, v81, v82
	v_max3_f32 v252, v252, v83, v84
	s_waitcnt lgkmcnt(2)
	v_mfma_f32_32x32x16_bf16 v[16:31], v[238:241], v[152:155], v[16:31]
	v_max3_f32 v252, v252, v85, v86
	v_max3_f32 v252, v252, v87, v88
	v_max3_f32 v252, v252, v89, v90
	v_max3_f32 v252, v252, v91, v92
	v_max3_f32 v252, v252, v93, v94
	v_max_f32_e32 v252, v252, v95
	v_max_f32_e32 v251, v251, v252
	v_mov_b32_e32 v252, v251
	s_nop 1
	v_permlane32_swap_b32_e32 v251, v252
	v_max_f32_e32 v251, v251, v252
	v_cmp_lt_f32_e32 vcc, 0x41000000, v251
	s_cmp_lg_u32 s26, 0
	s_cbranch_scc0 .Lmla_nr1b
	s_cbranch_vccnz .Lmla_rare1b

.Lmla_skip0b:
	s_waitcnt vmcnt(2)
	ds_write_b128 v205, v[120:123] offset:0
	ds_write_b128 v206, v[124:127] offset:38912
	s_waitcnt lgkmcnt(0)
	s_barrier
	s_branch .Lmla_end0b

.Lmla_skip1b:
	s_waitcnt vmcnt(2)
	ds_write_b128 v205, v[6:9] offset:25600
	ds_write_b128 v206, v[10:13] offset:13312
	s_waitcnt lgkmcnt(0)
	s_barrier
	s_branch .Lmla_end1b
